# v21 + RG-LRU gate GEMM: the 8 A-fragment ds_read_b128 issued ahead into distinct registers (counted lgkmcnt) instead of read-wait-MFMA serialized on one register
# speedup vs baseline: 1.0065x; 1.0065x over previous
; #define LAS __attribute__((address_space(3)))
; __device__ __forceinline__ float bf2f(unsigned b) { return __uint_as_float(b << 16); }
; __device__ __forceinline__ int crow(int reg, int h) { return (reg & 3) + 8 * (reg >> 2) + 4 * h; }
; #define MFMA32(a, b, c) __builtin_amdgcn_mfma_f32_32x32x16_bf16((a), (b), (c), 0, 0, 0)
; template <int MODE> __device__ __forceinline__ void lru_phase(const Params& P, LAS unsigned char* lds, int l, int tid_in) {
;     ...
;         if (cur) {
;             f32x16 ar, ai;
; #pragma unroll
;             for (int i = 0; i < 16; ++i) { ar[i] = 0.f; ai[i] = 0.f; }
; #pragma unroll
;             for (int kk = 0; kk < 8; ++kk) {
;                 const bf16x8 a = *(const LAS bf16x8*)(xcb + (rb * 32 + l32) * 136 + kk * 16 + h * 8);
;                 ar = MFMA32(a, br[kk], ar); ai = MFMA32(a, bi[kk], ai);
;             }
; #pragma unroll
;             for (int i = 0; i < 16; ++i) {
;                 const int r = rb * 32 + crow(i, h);
;                 const float rr = __builtin_amdgcn_rcpf(1.f + __builtin_amdgcn_exp2f(ar[i] * -L2E + nba)), ii = __builtin_amdgcn_rcpf(1.f + __builtin_amdgcn_exp2f(ai[i] * -L2E + nbx));
;                 const float a = __builtin_amdgcn_exp2f(ca * rr), mult = __builtin_amdgcn_sqrtf(fmaxf(1.f - a * a, 0.f));
;                 sa[r * 128 + cgate] = a; sb[r * 128 + cgate] = mult * ii * bf2f(xcb[r * 136 + cgate]);
;             }
.LBB0_1184:
	s_waitcnt lgkmcnt(0)
	s_barrier
	s_lshl_b32 s0, s41, 16
	s_add_i32 s1, s0, 0
	s_and_b64 vcc, exec, s[48:49]
	s_cbranch_vccnz .LBB0_1186
	ds_read_b128 v[0:3], v239
	ds_read_b128 v[82:85], v239 offset:32
	ds_read_b128 v[186:189], v239 offset:64
	ds_read_b128 v[226:229], v239 offset:96
	ds_read_b128 v[242:245], v239 offset:128
	ds_read_b128 v[246:249], v239 offset:160
	s_waitcnt lgkmcnt(5)
	v_mfma_f32_32x32x16_bf16 v[16:31], v[0:3], v[48:51], 0
	v_mfma_f32_32x32x16_bf16 v[0:15], v[0:3], v[56:59], 0
	s_waitcnt lgkmcnt(4)
	v_mfma_f32_32x32x16_bf16 v[16:31], v[82:85], v[52:55], v[16:31]
	v_mfma_f32_32x32x16_bf16 v[0:15], v[82:85], v[60:63], v[0:15]
	ds_read_b128 v[82:85], v239 offset:192
	s_waitcnt lgkmcnt(4)
	v_mfma_f32_32x32x16_bf16 v[16:31], v[186:189], v[64:67], v[16:31]
	v_mfma_f32_32x32x16_bf16 v[0:15], v[186:189], v[72:75], v[0:15]
	ds_read_b128 v[186:189], v239 offset:224
	s_waitcnt lgkmcnt(4)
	v_mfma_f32_32x32x16_bf16 v[16:31], v[226:229], v[68:71], v[16:31]
	v_mfma_f32_32x32x16_bf16 v[0:15], v[226:229], v[76:79], v[0:15]
	s_waitcnt lgkmcnt(3)
	v_mfma_f32_32x32x16_bf16 v[16:31], v[242:245], v[88:91], v[16:31]
	v_mfma_f32_32x32x16_bf16 v[0:15], v[242:245], v[96:99], v[0:15]
	s_waitcnt lgkmcnt(2)
	v_mfma_f32_32x32x16_bf16 v[16:31], v[246:249], v[92:95], v[16:31]
	v_mfma_f32_32x32x16_bf16 v[0:15], v[246:249], v[100:103], v[0:15]
	s_waitcnt lgkmcnt(1)
	v_mfma_f32_32x32x16_bf16 v[16:31], v[82:85], v[104:107], v[16:31]
	v_mfma_f32_32x32x16_bf16 v[0:15], v[82:85], v[112:115], v[0:15]
	s_waitcnt lgkmcnt(0)
	v_mfma_f32_32x32x16_bf16 v[16:31], v[186:189], v[108:111], v[16:31]
	v_mfma_f32_32x32x16_bf16 v[0:15], v[186:189], v[116:119], v[0:15]
	s_nop 10
	v_fmamk_f32 v16, v16, 0xbfb8aa3b, v178
	v_exp_f32_e32 v16, v16
	v_fmamk_f32 v17, v17, 0xbfb8aa3b, v178
	v_exp_f32_e32 v17, v17
	ds_read_u16 v82, v240
	v_add_f32_e32 v16, 1.0, v16
	v_rcp_f32_e32 v16, v16
	v_fmamk_f32 v0, v0, 0xbfb8aa3b, v179
	v_exp_f32_e32 v0, v0
	v_add_f32_e32 v17, 1.0, v17
	v_mul_f32_e32 v16, v180, v16
	v_exp_f32_e32 v16, v16
	v_rcp_f32_e32 v17, v17
	v_add_f32_e32 v0, 1.0, v0
	v_rcp_f32_e32 v0, v0
	v_fma_f32 v80, -v16, v16, 1.0
	v_max_f32_e32 v80, 0, v80
	v_sqrt_f32_e32 v80, v80
	v_fmamk_f32 v1, v1, 0xbfb8aa3b, v179
	v_mul_f32_e32 v17, v180, v17
	v_exp_f32_e32 v1, v1
	v_exp_f32_e32 v17, v17
	v_mul_f32_e32 v0, v0, v80
	s_waitcnt lgkmcnt(0)
	v_lshlrev_b32_e32 v80, 16, v82
	v_lshl_add_u32 v83, v193, 2, s1
	v_mul_f32_e32 v0, v0, v80
	ds_write2st64_b32 v83, v16, v0 offset0:68 offset1:196
	v_add_f32_e32 v0, 1.0, v1
	v_fma_f32 v1, -v17, v17, 1.0
	v_max_f32_e32 v1, 0, v1
	ds_read_u16 v16, v240 offset:272
	v_fmamk_f32 v18, v18, 0xbfb8aa3b, v178
	v_rcp_f32_e32 v0, v0
	v_sqrt_f32_e32 v1, v1
	v_exp_f32_e32 v18, v18
	v_add_u32_e32 v80, 0x80, v193
	v_lshl_add_u32 v80, v80, 2, s1
	v_mul_f32_e32 v0, v0, v1
	s_waitcnt lgkmcnt(0)
	v_lshlrev_b32_e32 v1, 16, v16
	v_add_f32_e32 v16, 1.0, v18
	v_rcp_f32_e32 v16, v16
	v_mul_f32_e32 v0, v0, v1
	v_fmamk_f32 v1, v2, 0xbfb8aa3b, v179
	v_exp_f32_e32 v1, v1
	v_mul_f32_e32 v2, v180, v16
	v_exp_f32_e32 v2, v2
	ds_write2st64_b32 v80, v17, v0 offset0:68 offset1:196
	v_add_f32_e32 v0, 1.0, v1
	ds_read_u16 v16, v240 offset:544
	v_fma_f32 v1, -v2, v2, 1.0
	v_max_f32_e32 v1, 0, v1
	v_fmamk_f32 v17, v19, 0xbfb8aa3b, v178
	v_rcp_f32_e32 v0, v0
	v_sqrt_f32_e32 v1, v1
	v_exp_f32_e32 v17, v17
	v_add_u32_e32 v18, 0x100, v193
	v_lshl_add_u32 v18, v18, 2, s1
	v_mul_f32_e32 v0, v0, v1
	s_waitcnt lgkmcnt(0)
	v_lshlrev_b32_e32 v1, 16, v16
	v_add_f32_e32 v16, 1.0, v17
	v_rcp_f32_e32 v16, v16
	v_mul_f32_e32 v0, v0, v1
	v_fmamk_f32 v1, v3, 0xbfb8aa3b, v179
	v_exp_f32_e32 v1, v1
	v_mul_f32_e32 v3, v180, v16
	v_exp_f32_e32 v3, v3
	ds_write2st64_b32 v18, v2, v0 offset0:68 offset1:196
	v_add_f32_e32 v0, 1.0, v1
	ds_read_u16 v2, v240 offset:816
	v_fma_f32 v1, -v3, v3, 1.0
	v_max_f32_e32 v1, 0, v1
	v_fmamk_f32 v16, v20, 0xbfb8aa3b, v178
	v_rcp_f32_e32 v0, v0
	v_sqrt_f32_e32 v1, v1
	v_exp_f32_e32 v16, v16
	v_add_u32_e32 v17, 0x180, v193
	v_lshl_add_u32 v17, v17, 2, s1
	v_mul_f32_e32 v0, v0, v1
	s_waitcnt lgkmcnt(0)
	v_lshlrev_b32_e32 v1, 16, v2
	v_add_f32_e32 v2, 1.0, v16
	v_rcp_f32_e32 v2, v2
	v_mul_f32_e32 v0, v0, v1
	v_fmamk_f32 v1, v4, 0xbfb8aa3b, v179
	v_exp_f32_e32 v1, v1
	v_mul_f32_e32 v2, v180, v2
	v_exp_f32_e32 v2, v2
	ds_write2st64_b32 v17, v3, v0 offset0:68 offset1:196
	v_add_f32_e32 v0, 1.0, v1
	ds_read_u16 v3, v240 offset:2176
	v_fma_f32 v1, -v2, v2, 1.0
	v_max_f32_e32 v1, 0, v1
	v_fmamk_f32 v4, v21, 0xbfb8aa3b, v178
	v_rcp_f32_e32 v0, v0
	v_sqrt_f32_e32 v1, v1
	v_exp_f32_e32 v4, v4
	v_lshl_add_u32 v16, v194, 2, s1
	v_mul_f32_e32 v0, v0, v1
	s_waitcnt lgkmcnt(0)
	v_lshlrev_b32_e32 v1, 16, v3
	v_add_f32_e32 v3, 1.0, v4
	v_rcp_f32_e32 v3, v3
	v_mul_f32_e32 v0, v0, v1
	v_fmamk_f32 v1, v5, 0xbfb8aa3b, v179
	v_exp_f32_e32 v1, v1
	v_mul_f32_e32 v3, v180, v3
	v_exp_f32_e32 v3, v3
	ds_write2st64_b32 v16, v2, v0 offset0:68 offset1:196
	v_add_f32_e32 v0, 1.0, v1
	ds_read_u16 v2, v240 offset:2448
	v_fma_f32 v1, -v3, v3, 1.0
	v_max_f32_e32 v1, 0, v1
	v_fmamk_f32 v4, v22, 0xbfb8aa3b, v178
	v_rcp_f32_e32 v0, v0
	v_sqrt_f32_e32 v1, v1
	v_exp_f32_e32 v4, v4
	v_lshl_add_u32 v5, v195, 2, s1
	v_mul_f32_e32 v0, v0, v1
	s_waitcnt lgkmcnt(0)
; __device__ __forceinline__ float bf2f(unsigned b) { return __uint_as_float(b << 16); }
; __device__ __forceinline__ int crow(int reg, int h) { return (reg & 3) + 8 * (reg >> 2) + 4 * h; }
; template <int MODE> __device__ __forceinline__ void lru_phase(const Params& P, LAS unsigned char* lds, int l, int tid_in) {
;     ...
; #pragma unroll
;             for (int i = 0; i < 16; ++i) {
;                 const int r = rb * 32 + crow(i, h);
;                 const float rr = __builtin_amdgcn_rcpf(1.f + __builtin_amdgcn_exp2f(ar[i] * -L2E + nba)), ii = __builtin_amdgcn_rcpf(1.f + __builtin_amdgcn_exp2f(ai[i] * -L2E + nbx));
;                 const float a = __builtin_amdgcn_exp2f(ca * rr), mult = __builtin_amdgcn_sqrtf(fmaxf(1.f - a * a, 0.f));
;                 sa[r * 128 + cgate] = a; sb[r * 128 + cgate] = mult * ii * bf2f(xcb[r * 136 + cgate]);
;             }
	v_lshlrev_b32_e32 v1, 16, v2
	v_add_f32_e32 v2, 1.0, v4
	v_rcp_f32_e32 v2, v2
	v_mul_f32_e32 v0, v0, v1
	v_fmamk_f32 v1, v6, 0xbfb8aa3b, v179
	v_exp_f32_e32 v1, v1
	v_mul_f32_e32 v2, v180, v2
	v_exp_f32_e32 v2, v2
	ds_write2st64_b32 v5, v3, v0 offset0:68 offset1:196
	v_add_f32_e32 v0, 1.0, v1
	ds_read_u16 v3, v240 offset:2720
	v_fma_f32 v1, -v2, v2, 1.0
	v_max_f32_e32 v1, 0, v1
	v_fmamk_f32 v4, v23, 0xbfb8aa3b, v178
	v_rcp_f32_e32 v0, v0
	v_sqrt_f32_e32 v1, v1
	v_exp_f32_e32 v4, v4
	v_lshl_add_u32 v5, v196, 2, s1
	v_fmamk_f32 v6, v31, 0xbfb8aa3b, v178
	v_mul_f32_e32 v0, v0, v1
	s_waitcnt lgkmcnt(0)
	v_lshlrev_b32_e32 v1, 16, v3
	v_add_f32_e32 v3, 1.0, v4
	v_rcp_f32_e32 v3, v3
	v_mul_f32_e32 v0, v0, v1
	v_fmamk_f32 v1, v7, 0xbfb8aa3b, v179
	v_exp_f32_e32 v1, v1
	v_mul_f32_e32 v3, v180, v3
	v_exp_f32_e32 v3, v3
	ds_write2st64_b32 v5, v2, v0 offset0:68 offset1:196
	v_add_f32_e32 v0, 1.0, v1
	ds_read_u16 v2, v240 offset:2992
	ds_read_u16 v7, v240 offset:7344
	v_fma_f32 v1, -v3, v3, 1.0
	v_max_f32_e32 v1, 0, v1
	v_fmamk_f32 v4, v24, 0xbfb8aa3b, v178
	v_rcp_f32_e32 v0, v0
	v_sqrt_f32_e32 v1, v1
	v_exp_f32_e32 v4, v4
	v_lshl_add_u32 v5, v197, 2, s1
	v_exp_f32_e32 v6, v6
	v_mul_f32_e32 v0, v0, v1
	s_waitcnt lgkmcnt(1)
	v_lshlrev_b32_e32 v1, 16, v2
	v_add_f32_e32 v2, 1.0, v4
	v_rcp_f32_e32 v2, v2
	v_mul_f32_e32 v0, v0, v1
	v_fmamk_f32 v1, v8, 0xbfb8aa3b, v179
	v_exp_f32_e32 v1, v1
	v_mul_f32_e32 v2, v180, v2
	v_exp_f32_e32 v2, v2
	ds_write2st64_b32 v5, v3, v0 offset0:68 offset1:196
	v_add_f32_e32 v0, 1.0, v1
	ds_read_u16 v3, v240 offset:4352
	v_fma_f32 v1, -v2, v2, 1.0
	v_max_f32_e32 v1, 0, v1
	v_fmamk_f32 v4, v25, 0xbfb8aa3b, v178
	v_rcp_f32_e32 v0, v0
	v_sqrt_f32_e32 v1, v1
	v_exp_f32_e32 v4, v4
	v_lshl_add_u32 v5, v198, 2, s1
	v_mul_f32_e32 v0, v0, v1
	s_waitcnt lgkmcnt(0)
	v_lshlrev_b32_e32 v1, 16, v3
	v_add_f32_e32 v3, 1.0, v4
	v_rcp_f32_e32 v3, v3
	v_mul_f32_e32 v0, v0, v1
	v_fmamk_f32 v1, v9, 0xbfb8aa3b, v179
	v_exp_f32_e32 v1, v1
	v_mul_f32_e32 v3, v180, v3
	v_exp_f32_e32 v3, v3
	ds_write2st64_b32 v5, v2, v0 offset0:68 offset1:196
	v_add_f32_e32 v0, 1.0, v1
	ds_read_u16 v2, v240 offset:4624
	v_fma_f32 v1, -v3, v3, 1.0
	v_max_f32_e32 v1, 0, v1
	v_fmamk_f32 v4, v26, 0xbfb8aa3b, v178
	v_rcp_f32_e32 v0, v0
	v_sqrt_f32_e32 v1, v1
	v_exp_f32_e32 v4, v4
	v_lshl_add_u32 v5, v199, 2, s1
	v_mul_f32_e32 v0, v0, v1
	s_waitcnt lgkmcnt(0)
	v_lshlrev_b32_e32 v1, 16, v2
	v_add_f32_e32 v2, 1.0, v4
	v_rcp_f32_e32 v2, v2
	v_mul_f32_e32 v0, v0, v1
	v_fmamk_f32 v1, v10, 0xbfb8aa3b, v179
	v_exp_f32_e32 v1, v1
	v_mul_f32_e32 v2, v180, v2
	v_exp_f32_e32 v2, v2
	ds_write2st64_b32 v5, v3, v0 offset0:68 offset1:196
	v_add_f32_e32 v0, 1.0, v1
	ds_read_u16 v3, v240 offset:4896
	v_fma_f32 v1, -v2, v2, 1.0
	v_max_f32_e32 v1, 0, v1
	v_fmamk_f32 v4, v27, 0xbfb8aa3b, v178
	v_rcp_f32_e32 v0, v0
	v_sqrt_f32_e32 v1, v1
	v_exp_f32_e32 v4, v4
	v_lshl_add_u32 v5, v200, 2, s1
	v_mul_f32_e32 v0, v0, v1
	s_waitcnt lgkmcnt(0)
	v_lshlrev_b32_e32 v1, 16, v3
	v_add_f32_e32 v3, 1.0, v4
	v_rcp_f32_e32 v3, v3
	v_mul_f32_e32 v0, v0, v1
	v_fmamk_f32 v1, v11, 0xbfb8aa3b, v179
	v_exp_f32_e32 v1, v1
	v_mul_f32_e32 v3, v180, v3
	v_exp_f32_e32 v3, v3
	ds_write2st64_b32 v5, v2, v0 offset0:68 offset1:196
	v_add_f32_e32 v0, 1.0, v1
	ds_read_u16 v2, v240 offset:5168
	v_fma_f32 v1, -v3, v3, 1.0
	v_max_f32_e32 v1, 0, v1
	v_fmamk_f32 v4, v28, 0xbfb8aa3b, v178
	v_rcp_f32_e32 v0, v0
	v_sqrt_f32_e32 v1, v1
	v_exp_f32_e32 v4, v4
	v_lshl_add_u32 v5, v201, 2, s1
	v_mul_f32_e32 v0, v0, v1
	s_waitcnt lgkmcnt(0)
	v_lshlrev_b32_e32 v1, 16, v2
	v_add_f32_e32 v2, 1.0, v4
	v_rcp_f32_e32 v2, v2
	v_mul_f32_e32 v0, v0, v1
	v_fmamk_f32 v1, v12, 0xbfb8aa3b, v179
	v_exp_f32_e32 v1, v1
	v_mul_f32_e32 v2, v180, v2
	v_exp_f32_e32 v2, v2
	ds_write2st64_b32 v5, v3, v0 offset0:68 offset1:196
	v_add_f32_e32 v0, 1.0, v1
	ds_read_u16 v3, v240 offset:6528
	v_fma_f32 v1, -v2, v2, 1.0
	v_max_f32_e32 v1, 0, v1
	v_fmamk_f32 v4, v29, 0xbfb8aa3b, v178
	v_rcp_f32_e32 v0, v0
	v_sqrt_f32_e32 v1, v1
	v_exp_f32_e32 v4, v4
	v_lshl_add_u32 v5, v202, 2, s1
	v_mul_f32_e32 v0, v0, v1
	s_waitcnt lgkmcnt(0)
	v_lshlrev_b32_e32 v1, 16, v3
	v_add_f32_e32 v3, 1.0, v4
	v_rcp_f32_e32 v3, v3
	v_mul_f32_e32 v0, v0, v1
	v_fmamk_f32 v1, v13, 0xbfb8aa3b, v179
	v_exp_f32_e32 v1, v1
	v_mul_f32_e32 v3, v180, v3
	v_exp_f32_e32 v3, v3
	ds_write2st64_b32 v5, v2, v0 offset0:68 offset1:196
	v_add_f32_e32 v0, 1.0, v1
	v_fmamk_f32 v2, v30, 0xbfb8aa3b, v178
	v_fma_f32 v1, -v3, v3, 1.0
	v_max_f32_e32 v1, 0, v1
	v_rcp_f32_e32 v0, v0
	v_sqrt_f32_e32 v1, v1
	v_exp_f32_e32 v2, v2
	ds_read_u16 v4, v240 offset:6800
	v_lshl_add_u32 v5, v203, 2, s1
	v_mul_f32_e32 v0, v0, v1
	v_add_f32_e32 v1, 1.0, v2
	v_rcp_f32_e32 v1, v1
	s_waitcnt lgkmcnt(0)
	v_lshlrev_b32_e32 v2, 16, v4
	v_fmamk_f32 v4, v14, 0xbfb8aa3b, v179
	v_exp_f32_e32 v4, v4
	v_mul_f32_e32 v1, v180, v1
	v_exp_f32_e32 v1, v1
	v_mul_f32_e32 v0, v0, v2
	ds_write2st64_b32 v5, v3, v0 offset0:68 offset1:196
	v_add_f32_e32 v3, 1.0, v6
	v_rcp_f32_e32 v3, v3
	v_add_f32_e32 v2, 1.0, v4
	v_fma_f32 v4, -v1, v1, 1.0
	v_max_f32_e32 v4, 0, v4
	v_rcp_f32_e32 v2, v2
	v_sqrt_f32_e32 v4, v4
	v_mul_f32_e32 v3, v180, v3
	v_fmamk_f32 v5, v15, 0xbfb8aa3b, v179
	v_exp_f32_e32 v3, v3
	v_exp_f32_e32 v5, v5
	v_mul_f32_e32 v2, v2, v4
	ds_read_u16 v4, v240 offset:7072
	v_fma_f32 v6, -v3, v3, 1.0
	v_add_f32_e32 v5, 1.0, v5
	v_max_f32_e32 v6, 0, v6
	v_rcp_f32_e32 v5, v5
	v_sqrt_f32_e32 v6, v6
	s_waitcnt lgkmcnt(0)
	v_lshlrev_b32_e32 v4, 16, v4
	v_lshl_add_u32 v0, v204, 2, s1
	v_mul_f32_e32 v2, v2, v4
	ds_write2st64_b32 v0, v1, v2 offset0:68 offset1:196
	v_mul_f32_e32 v1, v5, v6
	v_lshlrev_b32_e32 v2, 16, v7
	v_lshl_add_u32 v0, v205, 2, s1
	v_mul_f32_e32 v1, v1, v2
	ds_write2st64_b32 v0, v3, v1 offset0:68 offset1:196
